# weight-matrix cache warm-up stream before layer-0 proj GEMM
# speedup vs baseline: 1.0118x; 1.0118x over previous
.LBB0_326:
.LBB0_327:
	s_mul_i32 s98, s96, 0x30000
	v_lshrrev_b32_e32 v233, 6, v154
	v_mul_u32_u24_e32 v233, 0x6000, v233
	v_and_b32_e32 v234, 63, v154
	v_lshl_add_u32 v233, v234, 4, v233
	v_add_u32_e32 v233, s98, v233
	global_load_dwordx4 v[236:239], v233, s[90:91]
	global_load_dwordx4 v[236:239], v233, s[90:91] offset:1024
	global_load_dwordx4 v[236:239], v233, s[90:91] offset:2048
	global_load_dwordx4 v[236:239], v233, s[90:91] offset:3072
	v_add_u32_e32 v234, 0x1000, v233
	global_load_dwordx4 v[236:239], v234, s[90:91]
	global_load_dwordx4 v[236:239], v234, s[90:91] offset:1024
	global_load_dwordx4 v[236:239], v234, s[90:91] offset:2048
	global_load_dwordx4 v[236:239], v234, s[90:91] offset:3072
	v_add_u32_e32 v235, 0x1000, v234
	global_load_dwordx4 v[236:239], v235, s[90:91]
	global_load_dwordx4 v[236:239], v235, s[90:91] offset:1024
	global_load_dwordx4 v[236:239], v235, s[90:91] offset:2048
	global_load_dwordx4 v[236:239], v235, s[90:91] offset:3072
	v_add_u32_e32 v233, 0x1000, v235
	global_load_dwordx4 v[236:239], v233, s[90:91]
	global_load_dwordx4 v[236:239], v233, s[90:91] offset:1024
	global_load_dwordx4 v[236:239], v233, s[90:91] offset:2048
	global_load_dwordx4 v[236:239], v233, s[90:91] offset:3072
	v_add_u32_e32 v234, 0x1000, v233
	global_load_dwordx4 v[236:239], v234, s[90:91]
	global_load_dwordx4 v[236:239], v234, s[90:91] offset:1024
	global_load_dwordx4 v[236:239], v234, s[90:91] offset:2048
	global_load_dwordx4 v[236:239], v234, s[90:91] offset:3072
	v_add_u32_e32 v235, 0x1000, v234
	global_load_dwordx4 v[236:239], v235, s[90:91]
	global_load_dwordx4 v[236:239], v235, s[90:91] offset:1024
	global_load_dwordx4 v[236:239], v235, s[90:91] offset:2048
	global_load_dwordx4 v[236:239], v235, s[90:91] offset:3072
	s_waitcnt vmcnt(0)
	s_mov_b32 s33, s96
	v_mov_b32_e32 v11, v154
	s_cmpk_gt_i32 s33, 0x5ff
	v_readfirstlane_b32 s4, v11
	s_cbranch_scc1 .LBB0_357
	v_lshlrev_b32_e32 v1, 4, v11
	v_add_u32_e32 v2, 0x2000, v1
	v_ashrrev_i32_e32 v3, 31, v2
	v_lshrrev_b32_e32 v3, 22, v3
	v_add_u32_e32 v3, v2, v3
	v_ashrrev_i32_e32 v10, 10, v3
	v_mul_i32_i24_e32 v3, 0x400, v10
	v_sub_u32_e32 v2, v2, v3
	v_lshrrev_b32_e32 v3, 4, v2
	v_bitop3_b32 v2, v3, v2, 32 bitop3:0x6c
	v_ashrrev_i32_e32 v3, 31, v2
	v_lshrrev_b32_e32 v3, 26, v3
	v_add_u32_e32 v3, v2, v3
	v_lshlrev_b32_e32 v4, 3, v10
	v_ashrrev_i32_e32 v12, 6, v3
	v_and_b32_e32 v4, -16, v4
	v_add_u32_e32 v4, v12, v4
	v_and_b32_e32 v5, 3, v12
	s_mov_b32 s0, 0xfffe0
	v_lshrrev_b32_e32 v6, 2, v4
	v_lshlrev_b32_e32 v7, 1, v4
	v_and_b32_e32 v3, 0xc0, v3
	v_and_or_b32 v5, v4, s0, v5
	v_and_b32_e32 v6, 4, v6
	v_and_b32_e32 v7, 24, v7
	v_sub_u32_e32 v2, v2, v3
	v_mov_b32_e32 v3, 1
	v_or3_b32 v5, v5, v6, v7
	v_lshlrev_b32_e32 v6, 5, v10
	v_ashrrev_i16_sdwa v2, v3, sext(v2) dst_sel:DWORD dst_unused:UNUSED_PAD src0_sel:DWORD src1_sel:BYTE_0
	v_and_b32_e32 v6, 32, v6
	v_bfe_i32 v13, v2, 0, 16
	v_add_lshl_u32 v2, v6, v13, 1
	v_lshl_add_u32 v130, v5, 12, v2
	v_lshl_add_u32 v132, v4, 12, v2
	v_bfe_i32 v2, v11, 27, 1
	v_lshrrev_b32_e32 v2, 22, v2
	v_add_u32_e32 v2, v1, v2
	v_and_b32_e32 v2, 0xfffffc00, v2
	v_sub_u32_e32 v1, v1, v2
	v_lshrrev_b32_e32 v2, 4, v1
	v_bitop3_b32 v2, v2, v1, 32 bitop3:0x6c
	v_ashrrev_i32_e32 v1, 31, v1
	v_lshrrev_b32_e32 v1, 26, v1
	v_add_u32_e32 v1, v2, v1
	v_ashrrev_i32_e32 v14, 6, v1
	v_ashrrev_i32_e32 v1, 31, v11
	v_lshrrev_b32_e32 v1, 26, v1
	v_add_u32_e32 v1, v11, v1
	v_ashrrev_i32_e32 v15, 6, v1
	v_lshlrev_b32_e32 v1, 3, v15
	s_add_u32 s44, s90, 0x11918000
	v_and_b32_e32 v1, -16, v1
	s_addc_u32 s45, s91, 0
	v_add_u32_e32 v1, v14, v1
	v_and_b32_e32 v4, 3, v14
	s_ashr_i32 s47, s33, 31
	v_and_or_b32 v4, v1, s0, v4
	s_lshr_b32 s0, s47, 29
	s_add_i32 s0, s33, s0
	s_ashr_i32 s6, s4, 6
	s_ashr_i32 s1, s0, 3
	s_and_b32 s0, s0, -8
	s_ashr_i32 s5, s4, 8
	s_lshl_b32 s46, s6, 10
	s_sub_i32 s0, s33, s0
	s_cmp_lt_i32 s0, 0
	s_movk_i32 s48, 0xc1
	s_cselect_b32 s2, s48, 0xc0
	s_mul_i32 s0, s2, s0
	s_add_i32 s0, s0, s1
	s_mul_hi_i32 s1, s0, 0x2aaaaaab
	s_lshr_b32 s2, s1, 31
	s_ashr_i32 s1, s1, 6
	s_add_i32 s1, s1, s2
	s_lshl_b32 s2, s1, 3
	s_mulk_i32 s1, 0x180
	s_sub_i32 s0, s0, s1
	s_bfe_u32 s1, s0, 0x3001c
	s_add_i32 s1, s0, s1
	s_sext_i32_i16 s3, s1
	s_and_b32 s1, s1, 0xfff8
	s_sub_i32 s0, s0, s1
	s_sext_i32_i16 s0, s0
	s_ashr_i32 s66, s3, 3
	s_add_i32 s65, s2, s0
	s_sub_i32 s0, s66, 20
	s_cmp_lt_u32 s0, 12
	s_cselect_b64 s[0:1], -1, 0
	s_and_b64 s[2:3], s[0:1], exec
	s_cselect_b32 s2, s66, s65
	s_cselect_b32 s7, s91, s45
	s_cselect_b32 s8, s90, s44
	s_ashr_i32 s3, s2, 31
	s_lshl_b64 s[2:3], s[2:3], 20
	s_add_u32 s30, s8, s2
	v_lshrrev_b32_e32 v5, 2, v1
	v_lshlrev_b32_e32 v6, 1, v1
	s_addc_u32 s31, s7, s3
	v_and_b32_e32 v5, 4, v5
	v_and_b32_e32 v6, 24, v6
	s_and_b64 s[2:3], s[0:1], exec
	v_or3_b32 v4, v4, v5, v6
	v_mul_i32_i24_e32 v6, 64, v14
	s_cselect_b32 s2, s65, s66
	v_sub_u32_e32 v2, v2, v6
	s_cselect_b32 s7, s45, s91
	s_cselect_b32 s8, s44, s90
	s_ashr_i32 s3, s2, 31
	v_lshlrev_b32_e32 v5, 5, v15
	v_ashrrev_i16_sdwa v2, v3, sext(v2) dst_sel:DWORD dst_unused:UNUSED_PAD src0_sel:DWORD src1_sel:BYTE_0
	s_lshl_b64 s[2:3], s[2:3], 20
	v_and_b32_e32 v5, 32, v5
	v_bfe_i32 v16, v2, 0, 16
	s_add_u32 s38, s8, s2
	v_add_lshl_u32 v2, v5, v16, 1
	s_addc_u32 s39, s7, s3
	s_add_i32 s49, s46, 0
	v_lshl_add_u32 v134, v4, 12, v2
	s_add_i32 m0, s49, 0x10000
	v_lshl_add_u32 v136, v1, 12, v2
	global_load_lds_dwordx4 v134, s[38:39]
	s_add_i32 m0, s49, 0x12000
	s_add_u32 s2, s38, 0x80000
	global_load_lds_dwordx4 v130, s[38:39]
	s_addc_u32 s3, s39, 0
	s_add_i32 m0, s49, 0x14000
	s_add_i32 s50, s49, 0x2000
	global_load_lds_dwordx4 v134, s[2:3]
	s_add_i32 m0, s49, 0x16000
	v_mov_b32_e32 v135, 0
	global_load_lds_dwordx4 v130, s[2:3]
	s_mov_b32 m0, s49
	s_add_u32 s2, s30, 0x80000
	global_load_lds_dwordx4 v136, s[30:31]
	s_mov_b32 m0, s50
	s_addc_u32 s3, s31, 0
	s_add_i32 s51, s49, 0x4000
	global_load_lds_dwordx4 v132, s[30:31]
	s_mov_b32 m0, s51
	s_add_i32 s52, s49, 0x6000
	global_load_lds_dwordx4 v136, s[2:3]
	s_mov_b32 m0, s52
	v_mov_b32_e32 v131, v135
	global_load_lds_dwordx4 v132, s[2:3]
	v_mov_b32_e32 v137, v135
	v_mov_b32_e32 v133, v135
	s_cmp_eq_u32 s5, 1
	s_mov_b32 s42, 0
	v_lshl_add_u64 v[8:9], s[38:39], 0, v[134:135]
	v_lshl_add_u64 v[6:7], s[38:39], 0, v[130:131]
	v_lshl_add_u64 v[4:5], s[30:31], 0, v[136:137]
	v_lshl_add_u64 v[2:3], s[30:31], 0, v[132:133]
	s_cselect_b64 s[2:3], -1, 0
	s_cmp_lg_u32 s5, 1
	s_movk_i32 s53, 0x6000
	s_cbranch_scc1 .LBB0_330
	s_barrier

	.amdhsa_kernel _Z10fwd_kernel6Params
		.amdhsa_group_segment_fixed_size 0
		.amdhsa_private_segment_fixed_size 0
		.amdhsa_kernarg_size 520
		.amdhsa_user_sgpr_count 2
		.amdhsa_user_sgpr_dispatch_ptr 0
		.amdhsa_user_sgpr_queue_ptr 0
		.amdhsa_user_sgpr_kernarg_segment_ptr 1
		.amdhsa_user_sgpr_dispatch_id 0
		.amdhsa_user_sgpr_kernarg_preload_length 0
		.amdhsa_user_sgpr_kernarg_preload_offset 0
		.amdhsa_user_sgpr_private_segment_size 0
		.amdhsa_uses_dynamic_stack 0
		.amdhsa_enable_private_segment 0
		.amdhsa_system_sgpr_workgroup_id_x 1
		.amdhsa_system_sgpr_workgroup_id_y 0
		.amdhsa_system_sgpr_workgroup_id_z 0
		.amdhsa_system_sgpr_workgroup_info 0
		.amdhsa_system_vgpr_workitem_id 2
		.amdhsa_next_free_vgpr 240
		.amdhsa_next_free_sgpr 100
		.amdhsa_accum_offset 240
		.amdhsa_reserve_vcc 1
		.amdhsa_float_round_mode_32 0
		.amdhsa_float_round_mode_16_64 0
		.amdhsa_float_denorm_mode_32 3
		.amdhsa_float_denorm_mode_16_64 3
		.amdhsa_dx10_clamp 1
		.amdhsa_ieee_mode 1
		.amdhsa_fp16_overflow 0
		.amdhsa_tg_split 0
		.amdhsa_exception_fp_ieee_invalid_op 0
		.amdhsa_exception_fp_denorm_src 0
		.amdhsa_exception_fp_ieee_div_zero 0
		.amdhsa_exception_fp_ieee_overflow 0
		.amdhsa_exception_fp_ieee_underflow 0
		.amdhsa_exception_fp_ieee_inexact 0
		.amdhsa_exception_int_div_zero 0
	.end_amdhsa_kernel

amdhsa.kernels:
  - .agpr_count:     0
    .args:
      - .offset:         0
        .size:           264
        .value_kind:     by_value
      - .offset:         264
        .size:           4
        .value_kind:     hidden_block_count_x
      - .offset:         268
        .size:           4
        .value_kind:     hidden_block_count_y
      - .offset:         272
        .size:           4
        .value_kind:     hidden_block_count_z
      - .offset:         276
        .size:           2
        .value_kind:     hidden_group_size_x
      - .offset:         278
        .size:           2
        .value_kind:     hidden_group_size_y
      - .offset:         280
        .size:           2
        .value_kind:     hidden_group_size_z
      - .offset:         282
        .size:           2
        .value_kind:     hidden_remainder_x
      - .offset:         284
        .size:           2
        .value_kind:     hidden_remainder_y
      - .offset:         286
        .size:           2
        .value_kind:     hidden_remainder_z
      - .offset:         304
        .size:           8
        .value_kind:     hidden_global_offset_x
      - .offset:         312
        .size:           8
        .value_kind:     hidden_global_offset_y
      - .offset:         320
        .size:           8
        .value_kind:     hidden_global_offset_z
      - .offset:         328
        .size:           2
        .value_kind:     hidden_grid_dims
      - .offset:         352
        .size:           8
        .value_kind:     hidden_multigrid_sync_arg
      - .offset:         384
        .size:           4
        .value_kind:     hidden_dynamic_lds_size
    .group_segment_fixed_size: 0
    .kernarg_segment_align: 8
    .kernarg_segment_size: 520
    .language:       OpenCL C
    .language_version:
      - 2
      - 0
    .max_flat_workgroup_size: 512
    .name:           _Z10fwd_kernel6Params
    .private_segment_fixed_size: 0
    .sgpr_count:     106
    .sgpr_spill_count: 105
    .symbol:         _Z10fwd_kernel6Params.kd
    .uniform_work_group_size: 1
    .uses_dynamic_stack: false
    .vgpr_count:     240
    .vgpr_spill_count: 0
    .wavefront_size: 64
